# v40 plus, in the two 192-row K-loops only, the next load section's m0/base-pointer setup and the back-edge bookkeeping issued in front of the post-MFMA barrier (MFMA section has slack there)
# baseline (speedup 1.0000x reference)
; #define PG8_STAGE(bufoff, gbase, voff) do { _Pragma("unroll") for (int _i = 0; _i < 2; ++_i) \
;         __builtin_amdgcn_global_load_lds((const unsigned*)((const char*)(gbase) + (voff)[_i]), (LAS unsigned*)(lds + (bufoff) + ldsw + _i * 8192), 16, 0, 0); } while (0)
; #define PG8_LDA(dst, b, h) do { _Pragma("unroll") for (int m = 0; m < NM; ++m) _Pragma("unroll") for (int k = 0; k < 2; ++k) dst[m][k] = *(const LAS bf16x8*)(lds + PG8_SA(b, h) + aoff + m * 2048 + k * 1024); } while (0)
; #define PG8_MMA(ai, bj, At, Bt) do { __builtin_amdgcn_s_setprio(1); _Pragma("unroll") for (int m = 0; m < NM; ++m) _Pragma("unroll") for (int n = 0; n < 2; ++n) _Pragma("unroll") for (int k = 0; k < 2; ++k) \
;         acc[ai][bj][m][n] = __builtin_amdgcn_mfma_f32_16x16x32_bf16(Bt[n][k], At[m][k], acc[ai][bj][m][n], 0, 0, 0); __builtin_amdgcn_s_setprio(0); } while (0)
; #define PG8_WAIT_V(n) asm volatile("s_waitcnt vmcnt(" #n ")" ::: "memory")
; #define PG8_WAIT_L(n) asm volatile("s_waitcnt lgkmcnt(" #n ")" ::: "memory")
; #define PG8_BAR __builtin_amdgcn_s_barrier()
; #define PG8_SCHED __builtin_amdgcn_sched_barrier(0)
;     ...
;             PG8_WAIT_V(8); PG8_WAIT_L(0); PG8_BAR; PG8_MMA(0, 0, At, B0); PG8_MMA(0, 1, At, B1); PG8_BAR; PG8_SCHED;
;             PG8_LDA(At, 0, 1); PG8_STAGE(PG8_SB(0, 0), b2, voffB); PG8_STAGE(PG8_SB(0, 1), b2 + hstepB, voffB); PG8_STAGE(PG8_SA(0, 0), a2, voffA);
.Lnm3o_done0:
	s_waitcnt lgkmcnt(0)
	s_setprio 1
	s_barrier
	v_mfma_f32_16x16x32_bf16 v[110:113], v[90:93], v[130:133], v[110:113]
	v_mfma_f32_16x16x32_bf16 v[106:109], v[98:101], v[130:133], v[106:109]
	v_mfma_f32_16x16x32_bf16 v[78:81], v[90:93], v[138:141], v[78:81]
	v_mfma_f32_16x16x32_bf16 v[74:77], v[98:101], v[138:141], v[74:77]
	v_mfma_f32_16x16x32_bf16 v[62:65], v[90:93], v[156:159], v[62:65]
	v_mfma_f32_16x16x32_bf16 v[58:61], v[98:101], v[156:159], v[58:61]
	v_mfma_f32_16x16x32_bf16 v[110:113], v[94:97], v[134:137], v[110:113]
	v_mfma_f32_16x16x32_bf16 v[106:109], v[102:105], v[134:137], v[106:109]
	v_mfma_f32_16x16x32_bf16 v[78:81], v[94:97], v[152:155], v[78:81]
	v_mfma_f32_16x16x32_bf16 v[74:77], v[102:105], v[152:155], v[74:77]
	v_mfma_f32_16x16x32_bf16 v[62:65], v[94:97], v[160:163], v[62:65]
	v_mfma_f32_16x16x32_bf16 v[58:61], v[102:105], v[160:163], v[58:61]
	s_setprio 0
	s_setprio 1
	v_mfma_f32_16x16x32_bf16 v[86:89], v[114:117], v[130:133], v[86:89]
	v_mfma_f32_16x16x32_bf16 v[82:85], v[122:125], v[130:133], v[82:85]
	v_mfma_f32_16x16x32_bf16 v[70:73], v[114:117], v[138:141], v[70:73]
	v_mfma_f32_16x16x32_bf16 v[66:69], v[122:125], v[138:141], v[66:69]
	v_mfma_f32_16x16x32_bf16 v[54:57], v[114:117], v[156:159], v[54:57]
	v_mfma_f32_16x16x32_bf16 v[50:53], v[122:125], v[156:159], v[50:53]
	v_mfma_f32_16x16x32_bf16 v[86:89], v[118:121], v[134:137], v[86:89]
	v_mfma_f32_16x16x32_bf16 v[82:85], v[126:129], v[134:137], v[82:85]
	v_mfma_f32_16x16x32_bf16 v[70:73], v[118:121], v[152:155], v[70:73]
	v_mfma_f32_16x16x32_bf16 v[66:69], v[126:129], v[152:155], v[66:69]
	v_mfma_f32_16x16x32_bf16 v[54:57], v[118:121], v[160:163], v[54:57]
	v_mfma_f32_16x16x32_bf16 v[50:53], v[126:129], v[160:163], v[50:53]
	s_mov_b32 m0, s29
	v_lshl_add_u64 v[164:165], s[22:23], 0, v[0:1]
	s_add_u32 s62, s22, 0x80000
	s_addc_u32 s63, s23, 0
	s_barrier
	s_setprio 0
	ds_read_b128 v[130:133], v167 offset:16384
	ds_read_b128 v[134:137], v167 offset:17408
	ds_read_b128 v[138:141], v167 offset:18432
	ds_read_b128 v[152:155], v167 offset:19456
	ds_read_b128 v[156:159], v167 offset:20480
	ds_read_b128 v[160:163], v167 offset:21504
	s_cmp_lg_u32 s100, 0
	s_cbranch_scc1 .Ltl_ou_0s
	global_load_lds_dwordx4 v0, s[22:23]
	v_lshl_add_u64 v[168:169], s[22:23], 0, v[146:147]
	s_mov_b32 m0, s30
	s_nop 0
	global_load_lds_dwordx4 v146, s[22:23]
	s_mov_b32 m0, s33
	v_lshl_add_u64 v[172:173], s[24:25], 0, v[144:145]
	global_load_lds_dwordx4 v0, s[62:63]
	s_mov_b32 m0, s34
	s_nop 0
	global_load_lds_dwordx4 v146, s[62:63]
	v_lshl_add_u64 v[170:171], s[24:25], 0, v[142:143]
	s_mov_b32 m0, s35
	s_nop 0
	global_load_lds_dwordx4 v142, s[24:25]
	s_mov_b32 m0, s36
	s_nop 0
	s_and_b64 vcc, exec, s[10:11]
	s_cbranch_vccz .Lnm3o_skip1
	global_load_lds_dwordx4 v144, s[24:25]
	s_waitcnt vmcnt(8)
	s_branch .Lnm3o_done1

; #define PG8_STAGE(bufoff, gbase, voff) do { _Pragma("unroll") for (int _i = 0; _i < 2; ++_i) \
;         __builtin_amdgcn_global_load_lds((const unsigned*)((const char*)(gbase) + (voff)[_i]), (LAS unsigned*)(lds + (bufoff) + ldsw + _i * 8192), 16, 0, 0); } while (0)
; #define PG8_LDA(dst, b, h) do { _Pragma("unroll") for (int m = 0; m < NM; ++m) _Pragma("unroll") for (int k = 0; k < 2; ++k) dst[m][k] = *(const LAS bf16x8*)(lds + PG8_SA(b, h) + aoff + m * 2048 + k * 1024); } while (0)
; #define PG8_MMA(ai, bj, At, Bt) do { __builtin_amdgcn_s_setprio(1); _Pragma("unroll") for (int m = 0; m < NM; ++m) _Pragma("unroll") for (int n = 0; n < 2; ++n) _Pragma("unroll") for (int k = 0; k < 2; ++k) \
;         acc[ai][bj][m][n] = __builtin_amdgcn_mfma_f32_16x16x32_bf16(Bt[n][k], At[m][k], acc[ai][bj][m][n], 0, 0, 0); __builtin_amdgcn_s_setprio(0); } while (0)
; #define PG8_WAIT_V(n) asm volatile("s_waitcnt vmcnt(" #n ")" ::: "memory")
; #define PG8_WAIT_L(n) asm volatile("s_waitcnt lgkmcnt(" #n ")" ::: "memory")
; #define PG8_BAR __builtin_amdgcn_s_barrier()
; #define PG8_SCHED __builtin_amdgcn_sched_barrier(0)
;     ...
;             PG8_WAIT_V(8); PG8_WAIT_L(0); PG8_BAR; PG8_MMA(0, 0, At, B0); PG8_MMA(0, 1, At, B1); PG8_BAR; PG8_SCHED;
;             PG8_LDA(At, 1, 1); PG8_STAGE(PG8_SB(1, 0), b3, voffB); PG8_STAGE(PG8_SB(1, 1), b3 + hstepB, voffB); PG8_STAGE(PG8_SA(1, 0), a3, voffA);
.Ltl_ou_1d:
	s_waitcnt lgkmcnt(0)
	s_setprio 1
	s_barrier
	v_mfma_f32_16x16x32_bf16 v[110:113], v[90:93], v[130:133], v[110:113]
	v_mfma_f32_16x16x32_bf16 v[106:109], v[98:101], v[130:133], v[106:109]
	v_mfma_f32_16x16x32_bf16 v[78:81], v[90:93], v[138:141], v[78:81]
	v_mfma_f32_16x16x32_bf16 v[74:77], v[98:101], v[138:141], v[74:77]
	v_mfma_f32_16x16x32_bf16 v[62:65], v[90:93], v[156:159], v[62:65]
	v_mfma_f32_16x16x32_bf16 v[58:61], v[98:101], v[156:159], v[58:61]
	v_mfma_f32_16x16x32_bf16 v[110:113], v[94:97], v[134:137], v[110:113]
	v_mfma_f32_16x16x32_bf16 v[106:109], v[102:105], v[134:137], v[106:109]
	v_mfma_f32_16x16x32_bf16 v[78:81], v[94:97], v[152:155], v[78:81]
	v_mfma_f32_16x16x32_bf16 v[74:77], v[102:105], v[152:155], v[74:77]
	v_mfma_f32_16x16x32_bf16 v[62:65], v[94:97], v[160:163], v[62:65]
	v_mfma_f32_16x16x32_bf16 v[58:61], v[102:105], v[160:163], v[58:61]
	s_setprio 0
	s_setprio 1
	v_mfma_f32_16x16x32_bf16 v[86:89], v[114:117], v[130:133], v[86:89]
	v_mfma_f32_16x16x32_bf16 v[82:85], v[122:125], v[130:133], v[82:85]
	v_mfma_f32_16x16x32_bf16 v[70:73], v[114:117], v[138:141], v[70:73]
	v_mfma_f32_16x16x32_bf16 v[66:69], v[122:125], v[138:141], v[66:69]
	v_mfma_f32_16x16x32_bf16 v[54:57], v[114:117], v[156:159], v[54:57]
	v_mfma_f32_16x16x32_bf16 v[50:53], v[122:125], v[156:159], v[50:53]
	v_mfma_f32_16x16x32_bf16 v[86:89], v[118:121], v[134:137], v[86:89]
	v_mfma_f32_16x16x32_bf16 v[82:85], v[126:129], v[134:137], v[82:85]
	v_mfma_f32_16x16x32_bf16 v[70:73], v[118:121], v[152:155], v[70:73]
	v_mfma_f32_16x16x32_bf16 v[66:69], v[126:129], v[152:155], v[66:69]
	v_mfma_f32_16x16x32_bf16 v[54:57], v[118:121], v[160:163], v[54:57]
	v_mfma_f32_16x16x32_bf16 v[50:53], v[126:129], v[160:163], v[50:53]
	s_mov_b32 m0, s41
	v_lshl_add_u64 v[164:165], v[164:165], 0, s[66:67]
	s_add_u32 s22, s22, 0x80080
	s_addc_u32 s23, s23, 0
	s_barrier
	s_setprio 0
	ds_read_b128 v[130:133], v167 offset:49152
	ds_read_b128 v[134:137], v167 offset:50176
	ds_read_b128 v[138:141], v167 offset:51200
	ds_read_b128 v[152:155], v167 offset:52224
	ds_read_b128 v[156:159], v167 offset:53248
	ds_read_b128 v[160:163], v167 offset:54272
	s_cmp_lg_u32 s100, 0
	s_cbranch_scc1 .Ltl_ou_2s
	global_load_lds_dwordx4 v[164:165], off
	v_lshl_add_u64 v[164:165], v[168:169], 0, s[66:67]
	s_mov_b32 m0, s42
	s_nop 0
	global_load_lds_dwordx4 v[164:165], off
	s_mov_b32 m0, s46
	s_nop 0
	global_load_lds_dwordx4 v0, s[22:23]
	s_mov_b32 m0, s47
	s_nop 0
	global_load_lds_dwordx4 v146, s[22:23]
	v_lshl_add_u64 v[164:165], v[170:171], 0, s[66:67]
	s_mov_b32 m0, s43
	s_nop 0
	global_load_lds_dwordx4 v[164:165], off
	v_lshl_add_u64 v[164:165], v[172:173], 0, s[66:67]
	s_mov_b32 m0, s44
	s_nop 0
	s_and_b64 vcc, exec, s[10:11]
	s_cbranch_vccz .Lnm3o_skip3
	global_load_lds_dwordx4 v[164:165], off
	s_waitcnt vmcnt(8)
	s_branch .Lnm3o_done3

; #define PG8_MMA(ai, bj, At, Bt) do { __builtin_amdgcn_s_setprio(1); _Pragma("unroll") for (int m = 0; m < NM; ++m) _Pragma("unroll") for (int n = 0; n < 2; ++n) _Pragma("unroll") for (int k = 0; k < 2; ++k) \
;         acc[ai][bj][m][n] = __builtin_amdgcn_mfma_f32_16x16x32_bf16(Bt[n][k], At[m][k], acc[ai][bj][m][n], 0, 0, 0); __builtin_amdgcn_s_setprio(0); } while (0)
; #define PG8_WAIT_V(n) asm volatile("s_waitcnt vmcnt(" #n ")" ::: "memory")
; #define PG8_WAIT_L(n) asm volatile("s_waitcnt lgkmcnt(" #n ")" ::: "memory")
; #define PG8_BAR __builtin_amdgcn_s_barrier()
; #define PG8_SCHED __builtin_amdgcn_sched_barrier(0)
;     ...
;             PG8_WAIT_V(8); PG8_WAIT_L(0); PG8_BAR; PG8_MMA(1, 0, At, B0); PG8_MMA(1, 1, At, B1); PG8_BAR; PG8_SCHED;
;     ...
;         }
;         if constexpr (ALIGN_EPI) { if (wr == 0) PG8_BAR; }
.Ltl_ou_2d:
	s_waitcnt lgkmcnt(0)
	s_setprio 1
	s_barrier
	v_mfma_f32_16x16x32_bf16 v[46:49], v[90:93], v[130:133], v[46:49]
	v_mfma_f32_16x16x32_bf16 v[42:45], v[98:101], v[130:133], v[42:45]
	v_mfma_f32_16x16x32_bf16 v[30:33], v[90:93], v[138:141], v[30:33]
	v_mfma_f32_16x16x32_bf16 v[26:29], v[98:101], v[138:141], v[26:29]
	v_mfma_f32_16x16x32_bf16 v[14:17], v[90:93], v[156:159], v[14:17]
	v_mfma_f32_16x16x32_bf16 v[10:13], v[98:101], v[156:159], v[10:13]
	v_mfma_f32_16x16x32_bf16 v[46:49], v[94:97], v[134:137], v[46:49]
	v_mfma_f32_16x16x32_bf16 v[42:45], v[102:105], v[134:137], v[42:45]
	v_mfma_f32_16x16x32_bf16 v[30:33], v[94:97], v[152:155], v[30:33]
	v_mfma_f32_16x16x32_bf16 v[26:29], v[102:105], v[152:155], v[26:29]
	v_mfma_f32_16x16x32_bf16 v[14:17], v[94:97], v[160:163], v[14:17]
	v_mfma_f32_16x16x32_bf16 v[10:13], v[102:105], v[160:163], v[10:13]
	s_setprio 0
	s_setprio 1
	v_mfma_f32_16x16x32_bf16 v[38:41], v[114:117], v[130:133], v[38:41]
	v_mfma_f32_16x16x32_bf16 v[34:37], v[122:125], v[130:133], v[34:37]
	v_mfma_f32_16x16x32_bf16 v[22:25], v[114:117], v[138:141], v[22:25]
	v_mfma_f32_16x16x32_bf16 v[18:21], v[122:125], v[138:141], v[18:21]
	v_mfma_f32_16x16x32_bf16 v[6:9], v[114:117], v[156:159], v[6:9]
	v_mfma_f32_16x16x32_bf16 v[2:5], v[122:125], v[156:159], v[2:5]
	v_mfma_f32_16x16x32_bf16 v[38:41], v[118:121], v[134:137], v[38:41]
	v_mfma_f32_16x16x32_bf16 v[34:37], v[126:129], v[134:137], v[34:37]
	v_mfma_f32_16x16x32_bf16 v[22:25], v[118:121], v[152:155], v[22:25]
	v_mfma_f32_16x16x32_bf16 v[18:21], v[126:129], v[152:155], v[18:21]
	v_mfma_f32_16x16x32_bf16 v[6:9], v[118:121], v[160:163], v[6:9]
	v_mfma_f32_16x16x32_bf16 v[2:5], v[126:129], v[160:163], v[2:5]
	s_add_i32 s59, s59, 2
	s_add_u32 s8, s8, 0x100
	s_addc_u32 s9, s9, 0
	s_add_u32 s15, s15, 0x100
	s_addc_u32 s58, s58, 0
	s_cmp_gt_u32 s59, 29
	s_barrier
	s_setprio 0
	s_cbranch_scc0 .LBB0_1650
	s_and_b64 vcc, exec, s[10:11]
	s_cbranch_vccz .LBB0_1653
	s_barrier

; #define PG8_STAGE(bufoff, gbase, voff) do { _Pragma("unroll") for (int _i = 0; _i < 2; ++_i) \
;         __builtin_amdgcn_global_load_lds((const unsigned*)((const char*)(gbase) + (voff)[_i]), (LAS unsigned*)(lds + (bufoff) + ldsw + _i * 8192), 16, 0, 0); } while (0)
; #define PG8_LDA(dst, b, h) do { _Pragma("unroll") for (int m = 0; m < NM; ++m) _Pragma("unroll") for (int k = 0; k < 2; ++k) dst[m][k] = *(const LAS bf16x8*)(lds + PG8_SA(b, h) + aoff + m * 2048 + k * 1024); } while (0)
; #define PG8_MMA(ai, bj, At, Bt) do { __builtin_amdgcn_s_setprio(1); _Pragma("unroll") for (int m = 0; m < NM; ++m) _Pragma("unroll") for (int n = 0; n < 2; ++n) _Pragma("unroll") for (int k = 0; k < 2; ++k) \
;         acc[ai][bj][m][n] = __builtin_amdgcn_mfma_f32_16x16x32_bf16(Bt[n][k], At[m][k], acc[ai][bj][m][n], 0, 0, 0); __builtin_amdgcn_s_setprio(0); } while (0)
; #define PG8_WAIT_V(n) asm volatile("s_waitcnt vmcnt(" #n ")" ::: "memory")
; #define PG8_WAIT_L(n) asm volatile("s_waitcnt lgkmcnt(" #n ")" ::: "memory")
; #define PG8_BAR __builtin_amdgcn_s_barrier()
; #define PG8_SCHED __builtin_amdgcn_sched_barrier(0)
;     ...
;             PG8_WAIT_V(8); PG8_WAIT_L(0); PG8_BAR; PG8_MMA(0, 0, At, B0); PG8_MMA(0, 1, At, B1); PG8_BAR; PG8_SCHED;
;             PG8_LDA(At, 0, 1); PG8_STAGE(PG8_SB(0, 0), b2, voffB); PG8_STAGE(PG8_SB(0, 1), b2 + hstepB, voffB); PG8_STAGE(PG8_SA(0, 0), a2, voffA);
.Lnm3d_done0:
	s_waitcnt lgkmcnt(0)
	s_setprio 1
	s_barrier
	v_mfma_f32_16x16x32_bf16 v[110:113], v[90:93], v[130:133], v[110:113]
	v_mfma_f32_16x16x32_bf16 v[106:109], v[98:101], v[130:133], v[106:109]
	v_mfma_f32_16x16x32_bf16 v[78:81], v[90:93], v[138:141], v[78:81]
	v_mfma_f32_16x16x32_bf16 v[74:77], v[98:101], v[138:141], v[74:77]
	v_mfma_f32_16x16x32_bf16 v[62:65], v[90:93], v[156:159], v[62:65]
	v_mfma_f32_16x16x32_bf16 v[58:61], v[98:101], v[156:159], v[58:61]
	v_mfma_f32_16x16x32_bf16 v[110:113], v[94:97], v[134:137], v[110:113]
	v_mfma_f32_16x16x32_bf16 v[106:109], v[102:105], v[134:137], v[106:109]
	v_mfma_f32_16x16x32_bf16 v[78:81], v[94:97], v[152:155], v[78:81]
	v_mfma_f32_16x16x32_bf16 v[74:77], v[102:105], v[152:155], v[74:77]
	v_mfma_f32_16x16x32_bf16 v[62:65], v[94:97], v[160:163], v[62:65]
	v_mfma_f32_16x16x32_bf16 v[58:61], v[102:105], v[160:163], v[58:61]
	s_setprio 0
	s_setprio 1
	v_mfma_f32_16x16x32_bf16 v[86:89], v[114:117], v[130:133], v[86:89]
	v_mfma_f32_16x16x32_bf16 v[82:85], v[122:125], v[130:133], v[82:85]
	v_mfma_f32_16x16x32_bf16 v[70:73], v[114:117], v[138:141], v[70:73]
	v_mfma_f32_16x16x32_bf16 v[66:69], v[122:125], v[138:141], v[66:69]
	v_mfma_f32_16x16x32_bf16 v[54:57], v[114:117], v[156:159], v[54:57]
	v_mfma_f32_16x16x32_bf16 v[50:53], v[122:125], v[156:159], v[50:53]
	v_mfma_f32_16x16x32_bf16 v[86:89], v[118:121], v[134:137], v[86:89]
	v_mfma_f32_16x16x32_bf16 v[82:85], v[126:129], v[134:137], v[82:85]
	v_mfma_f32_16x16x32_bf16 v[70:73], v[118:121], v[152:155], v[70:73]
	v_mfma_f32_16x16x32_bf16 v[66:69], v[126:129], v[152:155], v[66:69]
	v_mfma_f32_16x16x32_bf16 v[54:57], v[118:121], v[160:163], v[54:57]
	v_mfma_f32_16x16x32_bf16 v[50:53], v[126:129], v[160:163], v[50:53]
	s_mov_b32 m0, s27
	v_lshl_add_u64 v[164:165], s[18:19], 0, v[0:1]
	s_add_u32 s14, s18, 0x160000
	s_addc_u32 s15, s19, 0
	s_barrier
	s_setprio 0
	ds_read_b128 v[130:133], v167 offset:16384
	ds_read_b128 v[134:137], v167 offset:17408
	ds_read_b128 v[138:141], v167 offset:18432
	ds_read_b128 v[152:155], v167 offset:19456
	ds_read_b128 v[156:159], v167 offset:20480
	ds_read_b128 v[160:163], v167 offset:21504
	s_cmp_lg_u32 s100, 0
	s_cbranch_scc1 .Ltl_dn_0s
	global_load_lds_dwordx4 v0, s[18:19]
	v_lshl_add_u64 v[168:169], s[18:19], 0, v[146:147]
	s_mov_b32 m0, s28
	s_nop 0
	global_load_lds_dwordx4 v146, s[18:19]
	s_mov_b32 m0, s30
	v_lshl_add_u64 v[172:173], s[20:21], 0, v[144:145]
	global_load_lds_dwordx4 v0, s[14:15]
	s_mov_b32 m0, s31
	s_nop 0
	global_load_lds_dwordx4 v146, s[14:15]
	v_lshl_add_u64 v[170:171], s[20:21], 0, v[142:143]
	s_mov_b32 m0, s34
	s_nop 0
	global_load_lds_dwordx4 v142, s[20:21]
	s_mov_b32 m0, s35
	s_nop 0
	s_and_b64 vcc, exec, s[8:9]
	s_cbranch_vccz .Lnm3d_skip1
	global_load_lds_dwordx4 v144, s[20:21]
	s_waitcnt vmcnt(8)
	s_branch .Lnm3d_done1

; #define PG8_STAGE(bufoff, gbase, voff) do { _Pragma("unroll") for (int _i = 0; _i < 2; ++_i) \
;         __builtin_amdgcn_global_load_lds((const unsigned*)((const char*)(gbase) + (voff)[_i]), (LAS unsigned*)(lds + (bufoff) + ldsw + _i * 8192), 16, 0, 0); } while (0)
; #define PG8_LDA(dst, b, h) do { _Pragma("unroll") for (int m = 0; m < NM; ++m) _Pragma("unroll") for (int k = 0; k < 2; ++k) dst[m][k] = *(const LAS bf16x8*)(lds + PG8_SA(b, h) + aoff + m * 2048 + k * 1024); } while (0)
; #define PG8_MMA(ai, bj, At, Bt) do { __builtin_amdgcn_s_setprio(1); _Pragma("unroll") for (int m = 0; m < NM; ++m) _Pragma("unroll") for (int n = 0; n < 2; ++n) _Pragma("unroll") for (int k = 0; k < 2; ++k) \
;         acc[ai][bj][m][n] = __builtin_amdgcn_mfma_f32_16x16x32_bf16(Bt[n][k], At[m][k], acc[ai][bj][m][n], 0, 0, 0); __builtin_amdgcn_s_setprio(0); } while (0)
; #define PG8_WAIT_V(n) asm volatile("s_waitcnt vmcnt(" #n ")" ::: "memory")
; #define PG8_WAIT_L(n) asm volatile("s_waitcnt lgkmcnt(" #n ")" ::: "memory")
; #define PG8_BAR __builtin_amdgcn_s_barrier()
; #define PG8_SCHED __builtin_amdgcn_sched_barrier(0)
;     ...
;             PG8_WAIT_V(8); PG8_WAIT_L(0); PG8_BAR; PG8_MMA(0, 0, At, B0); PG8_MMA(0, 1, At, B1); PG8_BAR; PG8_SCHED;
;             PG8_LDA(At, 1, 1); PG8_STAGE(PG8_SB(1, 0), b3, voffB); PG8_STAGE(PG8_SB(1, 1), b3 + hstepB, voffB); PG8_STAGE(PG8_SA(1, 0), a3, voffA);
.Ltl_dn_1d:
	s_waitcnt lgkmcnt(0)
	s_setprio 1
	s_barrier
	v_mfma_f32_16x16x32_bf16 v[110:113], v[90:93], v[130:133], v[110:113]
	v_mfma_f32_16x16x32_bf16 v[106:109], v[98:101], v[130:133], v[106:109]
	v_mfma_f32_16x16x32_bf16 v[78:81], v[90:93], v[138:141], v[78:81]
	v_mfma_f32_16x16x32_bf16 v[74:77], v[98:101], v[138:141], v[74:77]
	v_mfma_f32_16x16x32_bf16 v[62:65], v[90:93], v[156:159], v[62:65]
	v_mfma_f32_16x16x32_bf16 v[58:61], v[98:101], v[156:159], v[58:61]
	v_mfma_f32_16x16x32_bf16 v[110:113], v[94:97], v[134:137], v[110:113]
	v_mfma_f32_16x16x32_bf16 v[106:109], v[102:105], v[134:137], v[106:109]
	v_mfma_f32_16x16x32_bf16 v[78:81], v[94:97], v[152:155], v[78:81]
	v_mfma_f32_16x16x32_bf16 v[74:77], v[102:105], v[152:155], v[74:77]
	v_mfma_f32_16x16x32_bf16 v[62:65], v[94:97], v[160:163], v[62:65]
	v_mfma_f32_16x16x32_bf16 v[58:61], v[102:105], v[160:163], v[58:61]
	s_setprio 0
	s_setprio 1
	v_mfma_f32_16x16x32_bf16 v[86:89], v[114:117], v[130:133], v[86:89]
	v_mfma_f32_16x16x32_bf16 v[82:85], v[122:125], v[130:133], v[82:85]
	v_mfma_f32_16x16x32_bf16 v[70:73], v[114:117], v[138:141], v[70:73]
	v_mfma_f32_16x16x32_bf16 v[66:69], v[122:125], v[138:141], v[66:69]
	v_mfma_f32_16x16x32_bf16 v[54:57], v[114:117], v[156:159], v[54:57]
	v_mfma_f32_16x16x32_bf16 v[50:53], v[122:125], v[156:159], v[50:53]
	v_mfma_f32_16x16x32_bf16 v[86:89], v[118:121], v[134:137], v[86:89]
	v_mfma_f32_16x16x32_bf16 v[82:85], v[126:129], v[134:137], v[82:85]
	v_mfma_f32_16x16x32_bf16 v[70:73], v[118:121], v[152:155], v[70:73]
	v_mfma_f32_16x16x32_bf16 v[66:69], v[126:129], v[152:155], v[66:69]
	v_mfma_f32_16x16x32_bf16 v[54:57], v[118:121], v[160:163], v[54:57]
	v_mfma_f32_16x16x32_bf16 v[50:53], v[126:129], v[160:163], v[50:53]
	s_mov_b32 m0, s41
	v_lshl_add_u64 v[164:165], v[164:165], 0, s[66:67]
	s_add_u32 s14, s18, 0x160080
	s_addc_u32 s15, s19, 0
	s_barrier
	s_setprio 0
	ds_read_b128 v[130:133], v167 offset:49152
	ds_read_b128 v[134:137], v167 offset:50176
	ds_read_b128 v[138:141], v167 offset:51200
	ds_read_b128 v[152:155], v167 offset:52224
	ds_read_b128 v[156:159], v167 offset:53248
	ds_read_b128 v[160:163], v167 offset:54272
	s_cmp_lg_u32 s100, 0
	s_cbranch_scc1 .Ltl_dn_2s
	global_load_lds_dwordx4 v[164:165], off
	v_lshl_add_u64 v[164:165], v[168:169], 0, s[66:67]
	s_mov_b32 m0, s42
	s_nop 0
	global_load_lds_dwordx4 v[164:165], off
	s_mov_b32 m0, s46
	s_nop 0
	global_load_lds_dwordx4 v0, s[14:15]
	s_mov_b32 m0, s47
	s_nop 0
	global_load_lds_dwordx4 v146, s[14:15]
	v_lshl_add_u64 v[164:165], v[170:171], 0, s[66:67]
	s_mov_b32 m0, s43
	s_nop 0
	global_load_lds_dwordx4 v[164:165], off
	v_lshl_add_u64 v[164:165], v[172:173], 0, s[66:67]
	s_mov_b32 m0, s44
	s_nop 0
	s_and_b64 vcc, exec, s[8:9]
	s_cbranch_vccz .Lnm3d_skip3
	global_load_lds_dwordx4 v[164:165], off
	s_waitcnt vmcnt(8)
	s_branch .Lnm3d_done3

; #define PG8_MMA(ai, bj, At, Bt) do { __builtin_amdgcn_s_setprio(1); _Pragma("unroll") for (int m = 0; m < NM; ++m) _Pragma("unroll") for (int n = 0; n < 2; ++n) _Pragma("unroll") for (int k = 0; k < 2; ++k) \
;         acc[ai][bj][m][n] = __builtin_amdgcn_mfma_f32_16x16x32_bf16(Bt[n][k], At[m][k], acc[ai][bj][m][n], 0, 0, 0); __builtin_amdgcn_s_setprio(0); } while (0)
; #define PG8_WAIT_V(n) asm volatile("s_waitcnt vmcnt(" #n ")" ::: "memory")
; #define PG8_WAIT_L(n) asm volatile("s_waitcnt lgkmcnt(" #n ")" ::: "memory")
; #define PG8_BAR __builtin_amdgcn_s_barrier()
; #define PG8_SCHED __builtin_amdgcn_sched_barrier(0)
;     ...
;         for (int t = 0; t < nt; t += 2) {
;             const bool last = (t == nt - 2);
;             const char* a1 = cA + (size_t)(t + 1) * kstep;
;             const char* a2 = last ? nA : cA + (size_t)(t + 2) * kstep; const char* b2 = last ? nB : cB + (size_t)(t + 2) * kstep;
;     ...
;             PG8_WAIT_V(8); PG8_WAIT_L(0); PG8_BAR; PG8_MMA(1, 0, At, B0); PG8_MMA(1, 1, At, B1); PG8_BAR; PG8_SCHED;
.Ltl_dn_2d:
	s_waitcnt lgkmcnt(0)
	s_setprio 1
	s_barrier
	v_mfma_f32_16x16x32_bf16 v[46:49], v[90:93], v[130:133], v[46:49]
	v_mfma_f32_16x16x32_bf16 v[42:45], v[98:101], v[130:133], v[42:45]
	v_mfma_f32_16x16x32_bf16 v[30:33], v[90:93], v[138:141], v[30:33]
	v_mfma_f32_16x16x32_bf16 v[26:29], v[98:101], v[138:141], v[26:29]
	v_mfma_f32_16x16x32_bf16 v[14:17], v[90:93], v[156:159], v[14:17]
	v_mfma_f32_16x16x32_bf16 v[10:13], v[98:101], v[156:159], v[10:13]
	v_mfma_f32_16x16x32_bf16 v[46:49], v[94:97], v[134:137], v[46:49]
	v_mfma_f32_16x16x32_bf16 v[42:45], v[102:105], v[134:137], v[42:45]
	v_mfma_f32_16x16x32_bf16 v[30:33], v[94:97], v[152:155], v[30:33]
	v_mfma_f32_16x16x32_bf16 v[26:29], v[102:105], v[152:155], v[26:29]
	v_mfma_f32_16x16x32_bf16 v[14:17], v[94:97], v[160:163], v[14:17]
	v_mfma_f32_16x16x32_bf16 v[10:13], v[102:105], v[160:163], v[10:13]
	s_setprio 0
	s_setprio 1
	v_mfma_f32_16x16x32_bf16 v[38:41], v[114:117], v[130:133], v[38:41]
	v_mfma_f32_16x16x32_bf16 v[34:37], v[122:125], v[130:133], v[34:37]
	v_mfma_f32_16x16x32_bf16 v[22:25], v[114:117], v[138:141], v[22:25]
	v_mfma_f32_16x16x32_bf16 v[18:21], v[122:125], v[138:141], v[18:21]
	v_mfma_f32_16x16x32_bf16 v[6:9], v[114:117], v[156:159], v[6:9]
	v_mfma_f32_16x16x32_bf16 v[2:5], v[122:125], v[156:159], v[2:5]
	v_mfma_f32_16x16x32_bf16 v[38:41], v[118:121], v[134:137], v[38:41]
	v_mfma_f32_16x16x32_bf16 v[34:37], v[126:129], v[134:137], v[34:37]
	v_mfma_f32_16x16x32_bf16 v[22:25], v[118:121], v[152:155], v[22:25]
	v_mfma_f32_16x16x32_bf16 v[18:21], v[126:129], v[152:155], v[18:21]
	v_mfma_f32_16x16x32_bf16 v[6:9], v[118:121], v[160:163], v[6:9]
	v_mfma_f32_16x16x32_bf16 v[2:5], v[126:129], v[160:163], v[2:5]
	s_add_i32 s60, s60, 2
	s_add_u32 s2, s2, 0x100
	s_addc_u32 s3, s3, 0
	s_cmpk_gt_u32 s60, 0x55
	s_mov_b64 s[14:15], s[16:17]
	s_barrier
	s_setprio 0
	s_cbranch_scc0 .LBB0_2158
	s_and_b64 vcc, exec, s[8:9]
	s_cbranch_vccz .LBB0_2161
	s_barrier
